# P10: s_barrier in front of every sweep (U0 U1 V0 V1) of every round
# baseline (speedup 1.0000x reference)
.LBB0_1711:
	s_or_b64 exec, exec, s[10:11]
	s_barrier
	ds_read_u16 v0, v150
	ds_read_u16 v2, v150 offset:4
	ds_read_u16 v4, v150 offset:8
	ds_read_u16 v5, v150 offset:12
	ds_read_u16 v6, v210
	ds_read_u16 v7, v150 offset:256
	ds_read_u16 v8, v210 offset:256
	ds_read_u16 v48, v210 offset:512
	s_waitcnt lgkmcnt(7)
	v_and_b32_e32 v0, 0x3fff, v0
	v_lshlrev_b32_sdwa v68, v231, v0 dst_sel:DWORD dst_unused:UNUSED_PAD src0_sel:DWORD src1_sel:WORD_0
	s_waitcnt lgkmcnt(6)
	v_and_b32_e32 v2, 0x3fff, v2
	v_lshl_add_u64 v[0:1], v[76:77], 0, v[68:69]
	v_lshlrev_b32_sdwa v68, v231, v2 dst_sel:DWORD dst_unused:UNUSED_PAD src0_sel:DWORD src1_sel:WORD_0
	v_lshl_add_u64 v[2:3], v[76:77], 0, v[68:69]
	global_load_dwordx4 v[44:47], v[0:1], off offset:512
	global_load_dwordx4 v[40:43], v[2:3], off offset:512
	s_waitcnt lgkmcnt(5)
	v_and_b32_e32 v0, 0x3fff, v4
	v_lshlrev_b32_sdwa v68, v231, v0 dst_sel:DWORD dst_unused:UNUSED_PAD src0_sel:DWORD src1_sel:WORD_0
	s_waitcnt lgkmcnt(4)
	v_and_b32_e32 v2, 0x3fff, v5
	v_lshl_add_u64 v[0:1], v[76:77], 0, v[68:69]
	v_lshlrev_b32_sdwa v68, v231, v2 dst_sel:DWORD dst_unused:UNUSED_PAD src0_sel:DWORD src1_sel:WORD_0
	v_lshl_add_u64 v[2:3], v[76:77], 0, v[68:69]
	global_load_dwordx4 v[36:39], v[0:1], off offset:512
	global_load_dwordx4 v[32:35], v[2:3], off offset:512
	s_waitcnt lgkmcnt(3)
	v_and_b32_e32 v0, 0x3fff, v6
	v_lshlrev_b32_sdwa v2, v232, v0 dst_sel:DWORD dst_unused:UNUSED_PAD src0_sel:DWORD src1_sel:WORD_0
	s_waitcnt lgkmcnt(2)
	v_and_b32_e32 v0, 0x3fff, v7
	v_lshlrev_b32_sdwa v68, v231, v0 dst_sel:DWORD dst_unused:UNUSED_PAD src0_sel:DWORD src1_sel:WORD_0
	v_lshl_add_u64 v[0:1], v[76:77], 0, v[68:69]
	global_load_dword v104, v2, s[14:15]
	global_load_dword v103, v2, s[16:17]
	global_load_dwordx4 v[28:31], v[0:1], off offset:512
	ds_read_u16 v0, v150 offset:260
	ds_read_u16 v2, v150 offset:264
	ds_read_u16 v4, v150 offset:268
	ds_read_u16 v5, v150 offset:512
	ds_read_u16 v6, v150 offset:516
	ds_read_u16 v9, v150 offset:520
	ds_read_u16 v10, v150 offset:524
	s_waitcnt lgkmcnt(6)
	v_and_b32_e32 v0, 0x3fff, v0
	v_lshlrev_b32_sdwa v68, v231, v0 dst_sel:DWORD dst_unused:UNUSED_PAD src0_sel:DWORD src1_sel:WORD_0
	s_waitcnt lgkmcnt(5)
	v_and_b32_e32 v2, 0x3fff, v2
	v_lshl_add_u64 v[0:1], v[76:77], 0, v[68:69]
	v_lshlrev_b32_sdwa v68, v231, v2 dst_sel:DWORD dst_unused:UNUSED_PAD src0_sel:DWORD src1_sel:WORD_0
	v_lshl_add_u64 v[2:3], v[76:77], 0, v[68:69]
	global_load_dwordx4 v[20:23], v[0:1], off offset:512
	global_load_dwordx4 v[24:27], v[2:3], off offset:512
	s_waitcnt lgkmcnt(4)
	v_and_b32_e32 v0, 0x3fff, v4
	v_lshlrev_b32_sdwa v68, v231, v0 dst_sel:DWORD dst_unused:UNUSED_PAD src0_sel:DWORD src1_sel:WORD_0
	v_lshl_add_u64 v[0:1], v[76:77], 0, v[68:69]
	v_and_b32_e32 v2, 0x3fff, v8
	v_lshlrev_b32_sdwa v2, v232, v2 dst_sel:DWORD dst_unused:UNUSED_PAD src0_sel:DWORD src1_sel:WORD_0
	global_load_dwordx4 v[16:19], v[0:1], off offset:512
	global_load_dword v102, v2, s[14:15]
	global_load_dword v101, v2, s[16:17]
	s_waitcnt lgkmcnt(3)
	v_and_b32_e32 v0, 0x3fff, v5
	v_lshlrev_b32_sdwa v68, v231, v0 dst_sel:DWORD dst_unused:UNUSED_PAD src0_sel:DWORD src1_sel:WORD_0
	s_waitcnt lgkmcnt(2)
	v_and_b32_e32 v2, 0x3fff, v6
	v_lshl_add_u64 v[0:1], v[76:77], 0, v[68:69]
	v_lshlrev_b32_sdwa v68, v231, v2 dst_sel:DWORD dst_unused:UNUSED_PAD src0_sel:DWORD src1_sel:WORD_0
	v_lshl_add_u64 v[2:3], v[76:77], 0, v[68:69]
	global_load_dwordx4 v[12:15], v[0:1], off offset:512
	global_load_dwordx4 v[4:7], v[2:3], off offset:512
	s_waitcnt lgkmcnt(1)
	v_and_b32_e32 v0, 0x3fff, v9
	v_lshlrev_b32_sdwa v68, v231, v0 dst_sel:DWORD dst_unused:UNUSED_PAD src0_sel:DWORD src1_sel:WORD_0
	s_waitcnt lgkmcnt(0)
	v_and_b32_e32 v2, 0x3fff, v10
	v_lshl_add_u64 v[0:1], v[76:77], 0, v[68:69]
	v_lshlrev_b32_sdwa v68, v231, v2 dst_sel:DWORD dst_unused:UNUSED_PAD src0_sel:DWORD src1_sel:WORD_0
	v_and_b32_e32 v48, 0x3fff, v48
	v_lshl_add_u64 v[2:3], v[76:77], 0, v[68:69]
	v_lshlrev_b32_sdwa v48, v232, v48 dst_sel:DWORD dst_unused:UNUSED_PAD src0_sel:DWORD src1_sel:WORD_0
	global_load_dwordx4 v[8:11], v[0:1], off offset:512
	s_nop 0
	global_load_dwordx4 v[0:3], v[2:3], off offset:512
	s_nop 0
	global_load_dword v100, v48, s[14:15]
	global_load_dword v99, v48, s[16:17]
	v_add_u32_e32 v48, v210, v209
	ds_read2st64_b32 v[108:109], v48 offset0:4 offset1:6
	ds_read2st64_b32 v[110:111], v48 offset0:8 offset1:10
	ds_read2st64_b32 v[48:49], v48 offset0:12 offset1:14
	s_mov_b32 s34, -8
	v_mov_b32_e32 v105, v71
	v_mov_b32_e32 v106, v224
	s_waitcnt lgkmcnt(1)
	v_mov_b32_e32 v53, v111
	v_mov_b32_e32 v52, v108
	s_waitcnt lgkmcnt(0)
	v_mov_b32_e32 v51, v48
	v_mov_b32_e32 v50, v109
	v_mov_b32_e32 v48, v110
	s_branch .LBB0_1713

; __device__ __forceinline__ void phase10(const Args& a, LAS unsigned char* lds, int tid, int wave, int lane, int vcu, int G, int emask, bool probe) {
;     ...
;         float y[GTK][16];
; #pragma unroll
;         for (int tk = 0; tk < GTK; ++tk)
; #pragma unroll
;             for (int e = 0; e < 16; ++e) y[tk][e] = 0.f;
;         P10_SWEEPV(0, y);
.LBB0_1725:
	s_or_b64 exec, exec, s[10:11]
	s_barrier
	v_add_u32_e32 v151, v214, v75
	ds_read_u16 v0, v150
	ds_read_u16 v4, v151 offset:8
	ds_read_u16 v5, v151 offset:12
	ds_read_u16 v6, v151 offset:256
	ds_read_u16 v7, v151 offset:260
	ds_read_u16 v8, v151 offset:264
	ds_read_u16 v9, v151 offset:268
	ds_read_u16 v2, v213 offset:4
	s_waitcnt lgkmcnt(7)
	v_and_b32_e32 v0, 0x3fff, v0
	v_lshlrev_b32_sdwa v68, v231, v0 dst_sel:DWORD dst_unused:UNUSED_PAD src0_sel:DWORD src1_sel:WORD_0
	v_lshl_add_u64 v[0:1], v[78:79], 0, v[68:69]
	v_add_u32_e32 v152, 0x400, v214
	s_waitcnt lgkmcnt(0)
	v_and_b32_e32 v2, 0x3fff, v2
	v_lshlrev_b32_sdwa v68, v231, v2 dst_sel:DWORD dst_unused:UNUSED_PAD src0_sel:DWORD src1_sel:WORD_0
	v_lshl_add_u64 v[2:3], v[78:79], 0, v[68:69]
	global_load_dwordx4 v[40:43], v[0:1], off
	global_load_dwordx4 v[32:35], v[2:3], off
	v_and_b32_e32 v0, 0x3fff, v4
	v_lshlrev_b32_sdwa v68, v231, v0 dst_sel:DWORD dst_unused:UNUSED_PAD src0_sel:DWORD src1_sel:WORD_0
	v_and_b32_e32 v2, 0x3fff, v5
	v_lshl_add_u64 v[0:1], v[78:79], 0, v[68:69]
	v_lshlrev_b32_sdwa v68, v231, v2 dst_sel:DWORD dst_unused:UNUSED_PAD src0_sel:DWORD src1_sel:WORD_0
	v_lshl_add_u64 v[2:3], v[78:79], 0, v[68:69]
	global_load_dwordx4 v[44:47], v[0:1], off
	global_load_dwordx4 v[36:39], v[2:3], off
	v_and_b32_e32 v0, 0x3fff, v6
	v_lshlrev_b32_sdwa v68, v231, v0 dst_sel:DWORD dst_unused:UNUSED_PAD src0_sel:DWORD src1_sel:WORD_0
	v_and_b32_e32 v2, 0x3fff, v7
	v_lshl_add_u64 v[0:1], v[78:79], 0, v[68:69]
	v_lshlrev_b32_sdwa v68, v231, v2 dst_sel:DWORD dst_unused:UNUSED_PAD src0_sel:DWORD src1_sel:WORD_0
	v_lshl_add_u64 v[2:3], v[78:79], 0, v[68:69]
	global_load_dwordx4 v[20:23], v[0:1], off
	global_load_dwordx4 v[16:19], v[2:3], off
	v_and_b32_e32 v0, 0x3fff, v8
	v_lshlrev_b32_sdwa v68, v231, v0 dst_sel:DWORD dst_unused:UNUSED_PAD src0_sel:DWORD src1_sel:WORD_0
	v_and_b32_e32 v2, 0x3fff, v9
	ds_read_u16 v4, v151 offset:512
	v_lshl_add_u64 v[0:1], v[78:79], 0, v[68:69]
	v_lshlrev_b32_sdwa v68, v231, v2 dst_sel:DWORD dst_unused:UNUSED_PAD src0_sel:DWORD src1_sel:WORD_0
	v_lshl_add_u64 v[2:3], v[78:79], 0, v[68:69]
	global_load_dwordx4 v[28:31], v[0:1], off
	global_load_dwordx4 v[24:27], v[2:3], off
	ds_read_u16 v2, v151 offset:516
	ds_read_u16 v8, v151 offset:520
	ds_read_u16 v9, v151 offset:524
	s_waitcnt lgkmcnt(3)
	v_and_b32_e32 v0, 0x3fff, v4
	v_lshlrev_b32_sdwa v68, v231, v0 dst_sel:DWORD dst_unused:UNUSED_PAD src0_sel:DWORD src1_sel:WORD_0
	s_waitcnt lgkmcnt(2)
	v_and_b32_e32 v2, 0x3fff, v2
	v_lshl_add_u64 v[0:1], v[78:79], 0, v[68:69]
	v_lshlrev_b32_sdwa v68, v231, v2 dst_sel:DWORD dst_unused:UNUSED_PAD src0_sel:DWORD src1_sel:WORD_0
	v_lshl_add_u64 v[2:3], v[78:79], 0, v[68:69]
	global_load_dwordx4 v[12:15], v[0:1], off
	global_load_dwordx4 v[4:7], v[2:3], off
	s_waitcnt lgkmcnt(1)
	v_and_b32_e32 v0, 0x3fff, v8
	v_lshlrev_b32_sdwa v68, v231, v0 dst_sel:DWORD dst_unused:UNUSED_PAD src0_sel:DWORD src1_sel:WORD_0
	s_waitcnt lgkmcnt(0)
	v_and_b32_e32 v2, 0x3fff, v9
	v_lshl_add_u64 v[0:1], v[78:79], 0, v[68:69]
	v_lshlrev_b32_sdwa v68, v231, v2 dst_sel:DWORD dst_unused:UNUSED_PAD src0_sel:DWORD src1_sel:WORD_0
	v_lshl_add_u64 v[2:3], v[78:79], 0, v[68:69]
	global_load_dwordx4 v[8:11], v[0:1], off
	s_nop 0
	global_load_dwordx4 v[0:3], v[2:3], off
	v_add_u32_e32 v153, 0x600, v214
	ds_read_b32 v118, v67 offset:1024
	ds_read2_b32 v[148:149], v152 offset0:2 offset1:4
	ds_read2_b32 v[146:147], v152 offset0:6 offset1:128
	ds_read2_b32 v[144:145], v152 offset0:130 offset1:132
	ds_read2_b32 v[142:143], v153 offset0:6 offset1:128
	v_add_u32_e32 v154, 0x800, v214
	ds_read2_b32 v[140:141], v154 offset0:2 offset1:4
	ds_read_b32 v138, v214 offset:2072
	v_mov_b32_e32 v48, 0
	s_mov_b32 s10, -8
	v_mov_b32_e32 v139, v71
	v_mov_b32_e32 v155, v226
	s_waitcnt lgkmcnt(5)
	v_mov_b32_e32 v120, v149
	s_waitcnt lgkmcnt(3)
	v_mov_b32_e32 v98, v145
	v_mov_b32_e32 v102, v147
	s_waitcnt lgkmcnt(1)
	v_mov_b32_e32 v54, v141
	v_mov_b32_e32 v58, v143
	v_mov_b32_e32 v49, v48
	v_mov_b32_e32 v50, v48
	v_mov_b32_e32 v51, v48
	v_mov_b32_e32 v56, v48
	v_mov_b32_e32 v57, v48
	v_mov_b32_e32 v52, v48
	v_mov_b32_e32 v53, v48
	v_mov_b32_e32 v62, v48
	v_mov_b32_e32 v63, v48
	v_mov_b32_e32 v60, v48
	v_mov_b32_e32 v61, v48
	v_mov_b32_e32 v96, v48
	v_mov_b32_e32 v97, v48
	v_mov_b32_e32 v94, v48
	v_mov_b32_e32 v95, v48
	v_mov_b32_e32 v104, v48
	v_mov_b32_e32 v105, v48
	s_waitcnt vmcnt(13)
	v_mov_b32_e32 v100, v48
	v_mov_b32_e32 v101, v48
	v_mov_b32_e32 v108, v48
	v_mov_b32_e32 v109, v48
	v_mov_b32_e32 v106, v48
	v_mov_b32_e32 v107, v48
	v_mov_b32_e32 v112, v48
	v_mov_b32_e32 v113, v48
	v_mov_b32_e32 v110, v48
	v_mov_b32_e32 v111, v48
	v_mov_b32_e32 v116, v48
	v_mov_b32_e32 v117, v48
	v_mov_b32_e32 v114, v48
	v_mov_b32_e32 v115, v48
	v_mov_b32_e32 v124, v48
	v_mov_b32_e32 v125, v48
	v_mov_b32_e32 v122, v48
	v_mov_b32_e32 v123, v48
	v_mov_b32_e32 v128, v48
	v_mov_b32_e32 v129, v48
	v_mov_b32_e32 v126, v48
	v_mov_b32_e32 v127, v48
	v_mov_b32_e32 v132, v48
	v_mov_b32_e32 v133, v48
	v_mov_b32_e32 v130, v48
	v_mov_b32_e32 v131, v48
	v_mov_b32_e32 v136, v48
	v_mov_b32_e32 v137, v48
	v_mov_b32_e32 v134, v48
	v_mov_b32_e32 v135, v48
.LBB0_1726:
	s_waitcnt vmcnt(11)
	v_cvt_f32_i32_sdwa v157, sext(v40) dst_sel:DWORD dst_unused:UNUSED_PAD src0_sel:BYTE_1
	v_cvt_f32_i32_sdwa v156, sext(v40) dst_sel:DWORD dst_unused:UNUSED_PAD src0_sel:BYTE_0
	s_waitcnt vmcnt(10)
	v_cvt_f32_i32_sdwa v159, sext(v32) dst_sel:DWORD dst_unused:UNUSED_PAD src0_sel:BYTE_1
	v_cvt_f32_i32_sdwa v158, sext(v32) dst_sel:DWORD dst_unused:UNUSED_PAD src0_sel:BYTE_0
	s_waitcnt vmcnt(9)
	v_cvt_f32_i32_sdwa v161, sext(v44) dst_sel:DWORD dst_unused:UNUSED_PAD src0_sel:BYTE_1
	v_cvt_f32_i32_sdwa v160, sext(v44) dst_sel:DWORD dst_unused:UNUSED_PAD src0_sel:BYTE_0
	s_waitcnt vmcnt(8)
	v_cvt_f32_i32_sdwa v163, sext(v36) dst_sel:DWORD dst_unused:UNUSED_PAD src0_sel:BYTE_1
	v_cvt_f32_i32_sdwa v162, sext(v36) dst_sel:DWORD dst_unused:UNUSED_PAD src0_sel:BYTE_0
	v_cvt_f32_i32_sdwa v165, sext(v40) dst_sel:DWORD dst_unused:UNUSED_PAD src0_sel:BYTE_3
	v_cvt_f32_i32_sdwa v164, sext(v40) dst_sel:DWORD dst_unused:UNUSED_PAD src0_sel:BYTE_2
	v_cvt_f32_i32_sdwa v167, sext(v32) dst_sel:DWORD dst_unused:UNUSED_PAD src0_sel:BYTE_3
	v_cvt_f32_i32_sdwa v166, sext(v32) dst_sel:DWORD dst_unused:UNUSED_PAD src0_sel:BYTE_2
	v_cvt_f32_i32_sdwa v169, sext(v44) dst_sel:DWORD dst_unused:UNUSED_PAD src0_sel:BYTE_3
	v_cvt_f32_i32_sdwa v168, sext(v44) dst_sel:DWORD dst_unused:UNUSED_PAD src0_sel:BYTE_2
	v_cvt_f32_i32_sdwa v171, sext(v36) dst_sel:DWORD dst_unused:UNUSED_PAD src0_sel:BYTE_3
	v_cvt_f32_i32_sdwa v170, sext(v36) dst_sel:DWORD dst_unused:UNUSED_PAD src0_sel:BYTE_2
	v_cvt_f32_i32_sdwa v173, sext(v41) dst_sel:DWORD dst_unused:UNUSED_PAD src0_sel:BYTE_1
	v_cvt_f32_i32_sdwa v172, sext(v41) dst_sel:DWORD dst_unused:UNUSED_PAD src0_sel:BYTE_0
	v_cvt_f32_i32_sdwa v175, sext(v33) dst_sel:DWORD dst_unused:UNUSED_PAD src0_sel:BYTE_1
	v_cvt_f32_i32_sdwa v174, sext(v33) dst_sel:DWORD dst_unused:UNUSED_PAD src0_sel:BYTE_0
	v_cvt_f32_i32_sdwa v177, sext(v45) dst_sel:DWORD dst_unused:UNUSED_PAD src0_sel:BYTE_1
	v_cvt_f32_i32_sdwa v176, sext(v45) dst_sel:DWORD dst_unused:UNUSED_PAD src0_sel:BYTE_0
	v_cvt_f32_i32_sdwa v179, sext(v37) dst_sel:DWORD dst_unused:UNUSED_PAD src0_sel:BYTE_1
	v_cvt_f32_i32_sdwa v178, sext(v37) dst_sel:DWORD dst_unused:UNUSED_PAD src0_sel:BYTE_0
	v_cvt_f32_i32_sdwa v181, sext(v41) dst_sel:DWORD dst_unused:UNUSED_PAD src0_sel:BYTE_3
	v_cvt_f32_i32_sdwa v180, sext(v41) dst_sel:DWORD dst_unused:UNUSED_PAD src0_sel:BYTE_2
	v_cvt_f32_i32_sdwa v41, sext(v33) dst_sel:DWORD dst_unused:UNUSED_PAD src0_sel:BYTE_3
	v_cvt_f32_i32_sdwa v40, sext(v33) dst_sel:DWORD dst_unused:UNUSED_PAD src0_sel:BYTE_2
	v_cvt_f32_i32_sdwa v33, sext(v45) dst_sel:DWORD dst_unused:UNUSED_PAD src0_sel:BYTE_3
	v_cvt_f32_i32_sdwa v32, sext(v45) dst_sel:DWORD dst_unused:UNUSED_PAD src0_sel:BYTE_2
	v_cvt_f32_i32_sdwa v45, sext(v37) dst_sel:DWORD dst_unused:UNUSED_PAD src0_sel:BYTE_3
	v_cvt_f32_i32_sdwa v44, sext(v37) dst_sel:DWORD dst_unused:UNUSED_PAD src0_sel:BYTE_2
	v_cvt_f32_i32_sdwa v37, sext(v42) dst_sel:DWORD dst_unused:UNUSED_PAD src0_sel:BYTE_1
	v_cvt_f32_i32_sdwa v36, sext(v42) dst_sel:DWORD dst_unused:UNUSED_PAD src0_sel:BYTE_0
	v_cvt_f32_i32_sdwa v189, sext(v42) dst_sel:DWORD dst_unused:UNUSED_PAD src0_sel:BYTE_3
	v_cvt_f32_i32_sdwa v188, sext(v42) dst_sel:DWORD dst_unused:UNUSED_PAD src0_sel:BYTE_2
	v_cvt_f32_i32_sdwa v197, sext(v43) dst_sel:DWORD dst_unused:UNUSED_PAD src0_sel:BYTE_1
	v_cvt_f32_i32_sdwa v196, sext(v43) dst_sel:DWORD dst_unused:UNUSED_PAD src0_sel:BYTE_0
	v_cvt_f32_i32_sdwa v205, sext(v43) dst_sel:DWORD dst_unused:UNUSED_PAD src0_sel:BYTE_3
	v_cvt_f32_i32_sdwa v204, sext(v43) dst_sel:DWORD dst_unused:UNUSED_PAD src0_sel:BYTE_2
	v_cvt_f32_i32_sdwa v183, sext(v34) dst_sel:DWORD dst_unused:UNUSED_PAD src0_sel:BYTE_1
	v_cvt_f32_i32_sdwa v182, sext(v34) dst_sel:DWORD dst_unused:UNUSED_PAD src0_sel:BYTE_0
	v_cvt_f32_i32_sdwa v191, sext(v34) dst_sel:DWORD dst_unused:UNUSED_PAD src0_sel:BYTE_3
	v_cvt_f32_i32_sdwa v190, sext(v34) dst_sel:DWORD dst_unused:UNUSED_PAD src0_sel:BYTE_2
	v_cvt_f32_i32_sdwa v199, sext(v35) dst_sel:DWORD dst_unused:UNUSED_PAD src0_sel:BYTE_1
	v_cvt_f32_i32_sdwa v198, sext(v35) dst_sel:DWORD dst_unused:UNUSED_PAD src0_sel:BYTE_0
	v_cvt_f32_i32_sdwa v43, sext(v35) dst_sel:DWORD dst_unused:UNUSED_PAD src0_sel:BYTE_3
	v_cvt_f32_i32_sdwa v42, sext(v35) dst_sel:DWORD dst_unused:UNUSED_PAD src0_sel:BYTE_2
	v_cvt_f32_i32_sdwa v185, sext(v46) dst_sel:DWORD dst_unused:UNUSED_PAD src0_sel:BYTE_1
	v_cvt_f32_i32_sdwa v184, sext(v46) dst_sel:DWORD dst_unused:UNUSED_PAD src0_sel:BYTE_0
	v_cvt_f32_i32_sdwa v193, sext(v46) dst_sel:DWORD dst_unused:UNUSED_PAD src0_sel:BYTE_3
	v_cvt_f32_i32_sdwa v192, sext(v46) dst_sel:DWORD dst_unused:UNUSED_PAD src0_sel:BYTE_2
	v_cvt_f32_i32_sdwa v201, sext(v47) dst_sel:DWORD dst_unused:UNUSED_PAD src0_sel:BYTE_1
	v_cvt_f32_i32_sdwa v200, sext(v47) dst_sel:DWORD dst_unused:UNUSED_PAD src0_sel:BYTE_0
	v_cvt_f32_i32_sdwa v35, sext(v47) dst_sel:DWORD dst_unused:UNUSED_PAD src0_sel:BYTE_3
	v_cvt_f32_i32_sdwa v34, sext(v47) dst_sel:DWORD dst_unused:UNUSED_PAD src0_sel:BYTE_2
	v_cvt_f32_i32_sdwa v187, sext(v38) dst_sel:DWORD dst_unused:UNUSED_PAD src0_sel:BYTE_1
	v_cvt_f32_i32_sdwa v186, sext(v38) dst_sel:DWORD dst_unused:UNUSED_PAD src0_sel:BYTE_0
	v_cvt_f32_i32_sdwa v195, sext(v38) dst_sel:DWORD dst_unused:UNUSED_PAD src0_sel:BYTE_3
	v_cvt_f32_i32_sdwa v194, sext(v38) dst_sel:DWORD dst_unused:UNUSED_PAD src0_sel:BYTE_2
	v_cvt_f32_i32_sdwa v203, sext(v39) dst_sel:DWORD dst_unused:UNUSED_PAD src0_sel:BYTE_1
	v_cvt_f32_i32_sdwa v202, sext(v39) dst_sel:DWORD dst_unused:UNUSED_PAD src0_sel:BYTE_0
	v_cvt_f32_i32_sdwa v47, sext(v39) dst_sel:DWORD dst_unused:UNUSED_PAD src0_sel:BYTE_3
	v_cvt_f32_i32_sdwa v46, sext(v39) dst_sel:DWORD dst_unused:UNUSED_PAD src0_sel:BYTE_2
	v_pk_fma_f32 v[38:39], v[118:119], v[156:157], v[136:137] op_sel_hi:[0,1,1]
	v_pk_fma_f32 v[134:135], v[118:119], v[164:165], v[134:135] op_sel_hi:[0,1,1]
	v_pk_fma_f32 v[132:133], v[118:119], v[172:173], v[132:133] op_sel_hi:[0,1,1]
	v_pk_fma_f32 v[130:131], v[118:119], v[180:181], v[130:131] op_sel_hi:[0,1,1]
	v_pk_fma_f32 v[36:37], v[118:119], v[36:37], v[128:129] op_sel_hi:[0,1,1]
	v_pk_fma_f32 v[126:127], v[118:119], v[188:189], v[126:127] op_sel_hi:[0,1,1]
	v_pk_fma_f32 v[124:125], v[118:119], v[196:197], v[124:125] op_sel_hi:[0,1,1]
	v_pk_fma_f32 v[118:119], v[118:119], v[204:205], v[122:123] op_sel_hi:[0,1,1]
	v_pk_fma_f32 v[38:39], v[148:149], v[158:159], v[38:39] op_sel_hi:[0,1,1]
	v_pk_fma_f32 v[122:123], v[148:149], v[166:167], v[134:135] op_sel_hi:[0,1,1]
	v_pk_fma_f32 v[128:129], v[148:149], v[174:175], v[132:133] op_sel_hi:[0,1,1]
	v_pk_fma_f32 v[40:41], v[148:149], v[40:41], v[130:131] op_sel_hi:[0,1,1]
	v_pk_fma_f32 v[36:37], v[148:149], v[182:183], v[36:37] op_sel_hi:[0,1,1]
	v_pk_fma_f32 v[126:127], v[148:149], v[190:191], v[126:127] op_sel_hi:[0,1,1]
	v_pk_fma_f32 v[124:125], v[148:149], v[198:199], v[124:125] op_sel_hi:[0,1,1]
	v_pk_fma_f32 v[42:43], v[148:149], v[42:43], v[118:119] op_sel_hi:[0,1,1]
	v_pk_fma_f32 v[38:39], v[120:121], v[160:161], v[38:39] op_sel_hi:[0,1,1]
	v_pk_fma_f32 v[118:119], v[120:121], v[168:169], v[122:123] op_sel_hi:[0,1,1]
	v_pk_fma_f32 v[122:123], v[120:121], v[176:177], v[128:129] op_sel_hi:[0,1,1]
	v_pk_fma_f32 v[32:33], v[120:121], v[32:33], v[40:41] op_sel_hi:[0,1,1]
	v_pk_fma_f32 v[36:37], v[120:121], v[184:185], v[36:37] op_sel_hi:[0,1,1]
	v_pk_fma_f32 v[40:41], v[120:121], v[192:193], v[126:127] op_sel_hi:[0,1,1]
	v_pk_fma_f32 v[124:125], v[120:121], v[200:201], v[124:125] op_sel_hi:[0,1,1]
	v_pk_fma_f32 v[34:35], v[120:121], v[34:35], v[42:43] op_sel_hi:[0,1,1]
	v_pk_fma_f32 v[136:137], v[146:147], v[162:163], v[38:39] op_sel_hi:[0,1,1]
	v_pk_fma_f32 v[134:135], v[146:147], v[170:171], v[118:119] op_sel_hi:[0,1,1]
	v_pk_fma_f32 v[132:133], v[146:147], v[178:179], v[122:123] op_sel_hi:[0,1,1]
	v_pk_fma_f32 v[130:131], v[146:147], v[44:45], v[32:33] op_sel_hi:[0,1,1]
	v_pk_fma_f32 v[128:129], v[146:147], v[186:187], v[36:37] op_sel_hi:[0,1,1]
	v_pk_fma_f32 v[126:127], v[146:147], v[194:195], v[40:41] op_sel_hi:[0,1,1]
	v_pk_fma_f32 v[124:125], v[146:147], v[202:203], v[124:125] op_sel_hi:[0,1,1]
	v_pk_fma_f32 v[122:123], v[146:147], v[46:47], v[34:35] op_sel_hi:[0,1,1]
	ds_read_u16 v32, v139
	ds_read_u16 v33, v139 offset:4
	ds_read_u16 v36, v139 offset:8
	ds_read_u16 v38, v139 offset:12
	s_waitcnt lgkmcnt(3)
	v_and_b32_e32 v32, 0x3fff, v32
	s_waitcnt lgkmcnt(2)
	v_and_b32_e32 v34, 0x3fff, v33
	v_lshlrev_b32_sdwa v68, v231, v32 dst_sel:DWORD dst_unused:UNUSED_PAD src0_sel:DWORD src1_sel:WORD_0
	v_lshl_add_u64 v[32:33], v[78:79], 0, v[68:69]
	v_lshlrev_b32_sdwa v68, v231, v34 dst_sel:DWORD dst_unused:UNUSED_PAD src0_sel:DWORD src1_sel:WORD_0
	s_waitcnt lgkmcnt(1)
	v_and_b32_e32 v36, 0x3fff, v36
	v_lshl_add_u64 v[34:35], v[78:79], 0, v[68:69]
	v_lshlrev_b32_sdwa v68, v231, v36 dst_sel:DWORD dst_unused:UNUSED_PAD src0_sel:DWORD src1_sel:WORD_0
	s_waitcnt lgkmcnt(0)
	v_and_b32_e32 v38, 0x3fff, v38
	v_lshl_add_u64 v[36:37], v[78:79], 0, v[68:69]
	v_lshlrev_b32_sdwa v68, v231, v38 dst_sel:DWORD dst_unused:UNUSED_PAD src0_sel:DWORD src1_sel:WORD_0
	v_lshl_add_u64 v[38:39], v[78:79], 0, v[68:69]
	global_load_dwordx4 v[40:43], v[32:33], off
	s_nop 0
	global_load_dwordx4 v[32:35], v[34:35], off
	s_nop 0
	global_load_dwordx4 v[44:47], v[36:37], off
	s_nop 0
	global_load_dwordx4 v[36:39], v[38:39], off
	ds_read2_b32 v[118:119], v155 offset1:2
	ds_read2_b32 v[120:121], v155 offset0:4 offset1:6
	s_waitcnt vmcnt(11)
	v_cvt_f32_i32_sdwa v147, sext(v20) dst_sel:DWORD dst_unused:UNUSED_PAD src0_sel:BYTE_1
	v_cvt_f32_i32_sdwa v146, sext(v20) dst_sel:DWORD dst_unused:UNUSED_PAD src0_sel:BYTE_0
	s_waitcnt vmcnt(10)
	v_cvt_f32_i32_sdwa v149, sext(v16) dst_sel:DWORD dst_unused:UNUSED_PAD src0_sel:BYTE_1
	v_cvt_f32_i32_sdwa v148, sext(v16) dst_sel:DWORD dst_unused:UNUSED_PAD src0_sel:BYTE_0
	s_waitcnt vmcnt(9)
	v_cvt_f32_i32_sdwa v157, sext(v28) dst_sel:DWORD dst_unused:UNUSED_PAD src0_sel:BYTE_1
	v_cvt_f32_i32_sdwa v156, sext(v28) dst_sel:DWORD dst_unused:UNUSED_PAD src0_sel:BYTE_0
	s_waitcnt vmcnt(8)
	v_cvt_f32_i32_sdwa v159, sext(v24) dst_sel:DWORD dst_unused:UNUSED_PAD src0_sel:BYTE_1
	v_cvt_f32_i32_sdwa v158, sext(v24) dst_sel:DWORD dst_unused:UNUSED_PAD src0_sel:BYTE_0
	v_cvt_f32_i32_sdwa v161, sext(v20) dst_sel:DWORD dst_unused:UNUSED_PAD src0_sel:BYTE_3
	v_cvt_f32_i32_sdwa v160, sext(v20) dst_sel:DWORD dst_unused:UNUSED_PAD src0_sel:BYTE_2
	v_cvt_f32_i32_sdwa v163, sext(v16) dst_sel:DWORD dst_unused:UNUSED_PAD src0_sel:BYTE_3
	v_cvt_f32_i32_sdwa v162, sext(v16) dst_sel:DWORD dst_unused:UNUSED_PAD src0_sel:BYTE_2
	v_cvt_f32_i32_sdwa v165, sext(v28) dst_sel:DWORD dst_unused:UNUSED_PAD src0_sel:BYTE_3
	v_cvt_f32_i32_sdwa v164, sext(v28) dst_sel:DWORD dst_unused:UNUSED_PAD src0_sel:BYTE_2
	v_cvt_f32_i32_sdwa v167, sext(v24) dst_sel:DWORD dst_unused:UNUSED_PAD src0_sel:BYTE_3
	v_cvt_f32_i32_sdwa v166, sext(v24) dst_sel:DWORD dst_unused:UNUSED_PAD src0_sel:BYTE_2
	v_cvt_f32_i32_sdwa v169, sext(v21) dst_sel:DWORD dst_unused:UNUSED_PAD src0_sel:BYTE_1
	v_cvt_f32_i32_sdwa v168, sext(v21) dst_sel:DWORD dst_unused:UNUSED_PAD src0_sel:BYTE_0
	v_cvt_f32_i32_sdwa v171, sext(v17) dst_sel:DWORD dst_unused:UNUSED_PAD src0_sel:BYTE_1
	v_cvt_f32_i32_sdwa v170, sext(v17) dst_sel:DWORD dst_unused:UNUSED_PAD src0_sel:BYTE_0
	v_cvt_f32_i32_sdwa v173, sext(v29) dst_sel:DWORD dst_unused:UNUSED_PAD src0_sel:BYTE_1
	v_cvt_f32_i32_sdwa v172, sext(v29) dst_sel:DWORD dst_unused:UNUSED_PAD src0_sel:BYTE_0
	v_cvt_f32_i32_sdwa v175, sext(v25) dst_sel:DWORD dst_unused:UNUSED_PAD src0_sel:BYTE_1
	v_cvt_f32_i32_sdwa v174, sext(v25) dst_sel:DWORD dst_unused:UNUSED_PAD src0_sel:BYTE_0
	v_cvt_f32_i32_sdwa v177, sext(v21) dst_sel:DWORD dst_unused:UNUSED_PAD src0_sel:BYTE_3
	v_cvt_f32_i32_sdwa v176, sext(v21) dst_sel:DWORD dst_unused:UNUSED_PAD src0_sel:BYTE_2
	v_cvt_f32_i32_sdwa v21, sext(v17) dst_sel:DWORD dst_unused:UNUSED_PAD src0_sel:BYTE_3
	v_cvt_f32_i32_sdwa v20, sext(v17) dst_sel:DWORD dst_unused:UNUSED_PAD src0_sel:BYTE_2
	v_cvt_f32_i32_sdwa v17, sext(v29) dst_sel:DWORD dst_unused:UNUSED_PAD src0_sel:BYTE_3
	v_cvt_f32_i32_sdwa v16, sext(v29) dst_sel:DWORD dst_unused:UNUSED_PAD src0_sel:BYTE_2
	v_cvt_f32_i32_sdwa v29, sext(v25) dst_sel:DWORD dst_unused:UNUSED_PAD src0_sel:BYTE_3
	v_cvt_f32_i32_sdwa v28, sext(v25) dst_sel:DWORD dst_unused:UNUSED_PAD src0_sel:BYTE_2
	v_cvt_f32_i32_sdwa v25, sext(v22) dst_sel:DWORD dst_unused:UNUSED_PAD src0_sel:BYTE_1
	v_cvt_f32_i32_sdwa v24, sext(v22) dst_sel:DWORD dst_unused:UNUSED_PAD src0_sel:BYTE_0
	v_cvt_f32_i32_sdwa v185, sext(v22) dst_sel:DWORD dst_unused:UNUSED_PAD src0_sel:BYTE_3
	v_cvt_f32_i32_sdwa v184, sext(v22) dst_sel:DWORD dst_unused:UNUSED_PAD src0_sel:BYTE_2
	v_cvt_f32_i32_sdwa v193, sext(v23) dst_sel:DWORD dst_unused:UNUSED_PAD src0_sel:BYTE_1
	v_cvt_f32_i32_sdwa v192, sext(v23) dst_sel:DWORD dst_unused:UNUSED_PAD src0_sel:BYTE_0
	v_cvt_f32_i32_sdwa v201, sext(v23) dst_sel:DWORD dst_unused:UNUSED_PAD src0_sel:BYTE_3
	v_cvt_f32_i32_sdwa v200, sext(v23) dst_sel:DWORD dst_unused:UNUSED_PAD src0_sel:BYTE_2
	v_cvt_f32_i32_sdwa v179, sext(v18) dst_sel:DWORD dst_unused:UNUSED_PAD src0_sel:BYTE_1
	v_cvt_f32_i32_sdwa v178, sext(v18) dst_sel:DWORD dst_unused:UNUSED_PAD src0_sel:BYTE_0
	v_cvt_f32_i32_sdwa v187, sext(v18) dst_sel:DWORD dst_unused:UNUSED_PAD src0_sel:BYTE_3
	v_cvt_f32_i32_sdwa v186, sext(v18) dst_sel:DWORD dst_unused:UNUSED_PAD src0_sel:BYTE_2
	v_cvt_f32_i32_sdwa v195, sext(v19) dst_sel:DWORD dst_unused:UNUSED_PAD src0_sel:BYTE_1
	v_cvt_f32_i32_sdwa v194, sext(v19) dst_sel:DWORD dst_unused:UNUSED_PAD src0_sel:BYTE_0
	v_cvt_f32_i32_sdwa v23, sext(v19) dst_sel:DWORD dst_unused:UNUSED_PAD src0_sel:BYTE_3
	v_cvt_f32_i32_sdwa v22, sext(v19) dst_sel:DWORD dst_unused:UNUSED_PAD src0_sel:BYTE_2
	v_cvt_f32_i32_sdwa v181, sext(v30) dst_sel:DWORD dst_unused:UNUSED_PAD src0_sel:BYTE_1
	v_cvt_f32_i32_sdwa v180, sext(v30) dst_sel:DWORD dst_unused:UNUSED_PAD src0_sel:BYTE_0
	v_cvt_f32_i32_sdwa v189, sext(v30) dst_sel:DWORD dst_unused:UNUSED_PAD src0_sel:BYTE_3
	v_cvt_f32_i32_sdwa v188, sext(v30) dst_sel:DWORD dst_unused:UNUSED_PAD src0_sel:BYTE_2
	v_cvt_f32_i32_sdwa v197, sext(v31) dst_sel:DWORD dst_unused:UNUSED_PAD src0_sel:BYTE_1
	v_cvt_f32_i32_sdwa v196, sext(v31) dst_sel:DWORD dst_unused:UNUSED_PAD src0_sel:BYTE_0
	v_cvt_f32_i32_sdwa v19, sext(v31) dst_sel:DWORD dst_unused:UNUSED_PAD src0_sel:BYTE_3
	v_cvt_f32_i32_sdwa v18, sext(v31) dst_sel:DWORD dst_unused:UNUSED_PAD src0_sel:BYTE_2
	v_cvt_f32_i32_sdwa v183, sext(v26) dst_sel:DWORD dst_unused:UNUSED_PAD src0_sel:BYTE_1
	v_cvt_f32_i32_sdwa v182, sext(v26) dst_sel:DWORD dst_unused:UNUSED_PAD src0_sel:BYTE_0
	v_cvt_f32_i32_sdwa v191, sext(v26) dst_sel:DWORD dst_unused:UNUSED_PAD src0_sel:BYTE_3
	v_cvt_f32_i32_sdwa v190, sext(v26) dst_sel:DWORD dst_unused:UNUSED_PAD src0_sel:BYTE_2
	v_cvt_f32_i32_sdwa v199, sext(v27) dst_sel:DWORD dst_unused:UNUSED_PAD src0_sel:BYTE_1
	v_cvt_f32_i32_sdwa v198, sext(v27) dst_sel:DWORD dst_unused:UNUSED_PAD src0_sel:BYTE_0
	v_cvt_f32_i32_sdwa v31, sext(v27) dst_sel:DWORD dst_unused:UNUSED_PAD src0_sel:BYTE_3
	v_cvt_f32_i32_sdwa v30, sext(v27) dst_sel:DWORD dst_unused:UNUSED_PAD src0_sel:BYTE_2
	v_pk_fma_f32 v[26:27], v[102:103], v[146:147], v[116:117] op_sel_hi:[0,1,1]
	v_pk_fma_f32 v[114:115], v[102:103], v[160:161], v[114:115] op_sel_hi:[0,1,1]
	v_pk_fma_f32 v[112:113], v[102:103], v[168:169], v[112:113] op_sel_hi:[0,1,1]
	v_pk_fma_f32 v[110:111], v[102:103], v[176:177], v[110:111] op_sel_hi:[0,1,1]
	v_pk_fma_f32 v[24:25], v[102:103], v[24:25], v[108:109] op_sel_hi:[0,1,1]
	v_pk_fma_f32 v[106:107], v[102:103], v[184:185], v[106:107] op_sel_hi:[0,1,1]
	v_pk_fma_f32 v[104:105], v[102:103], v[192:193], v[104:105] op_sel_hi:[0,1,1]
	v_pk_fma_f32 v[100:101], v[102:103], v[200:201], v[100:101] op_sel_hi:[0,1,1]
	v_pk_fma_f32 v[26:27], v[144:145], v[148:149], v[26:27] op_sel_hi:[0,1,1]
	v_pk_fma_f32 v[102:103], v[144:145], v[162:163], v[114:115] op_sel_hi:[0,1,1]
	v_pk_fma_f32 v[108:109], v[144:145], v[170:171], v[112:113] op_sel_hi:[0,1,1]
	v_pk_fma_f32 v[20:21], v[144:145], v[20:21], v[110:111] op_sel_hi:[0,1,1]
	v_pk_fma_f32 v[24:25], v[144:145], v[178:179], v[24:25] op_sel_hi:[0,1,1]
	v_pk_fma_f32 v[106:107], v[144:145], v[186:187], v[106:107] op_sel_hi:[0,1,1]
	v_pk_fma_f32 v[104:105], v[144:145], v[194:195], v[104:105] op_sel_hi:[0,1,1]
	v_pk_fma_f32 v[22:23], v[144:145], v[22:23], v[100:101] op_sel_hi:[0,1,1]
	v_pk_fma_f32 v[26:27], v[98:99], v[156:157], v[26:27] op_sel_hi:[0,1,1]
	v_pk_fma_f32 v[100:101], v[98:99], v[164:165], v[102:103] op_sel_hi:[0,1,1]
	v_pk_fma_f32 v[102:103], v[98:99], v[172:173], v[108:109] op_sel_hi:[0,1,1]
	v_pk_fma_f32 v[16:17], v[98:99], v[16:17], v[20:21] op_sel_hi:[0,1,1]
	v_pk_fma_f32 v[20:21], v[98:99], v[180:181], v[24:25] op_sel_hi:[0,1,1]
	v_pk_fma_f32 v[24:25], v[98:99], v[188:189], v[106:107] op_sel_hi:[0,1,1]
	v_pk_fma_f32 v[104:105], v[98:99], v[196:197], v[104:105] op_sel_hi:[0,1,1]
	v_pk_fma_f32 v[18:19], v[98:99], v[18:19], v[22:23] op_sel_hi:[0,1,1]
	v_pk_fma_f32 v[116:117], v[142:143], v[158:159], v[26:27] op_sel_hi:[0,1,1]
	v_pk_fma_f32 v[114:115], v[142:143], v[166:167], v[100:101] op_sel_hi:[0,1,1]
	v_pk_fma_f32 v[112:113], v[142:143], v[174:175], v[102:103] op_sel_hi:[0,1,1]
	v_pk_fma_f32 v[110:111], v[142:143], v[28:29], v[16:17] op_sel_hi:[0,1,1]
	v_pk_fma_f32 v[108:109], v[142:143], v[182:183], v[20:21] op_sel_hi:[0,1,1]
	v_pk_fma_f32 v[106:107], v[142:143], v[190:191], v[24:25] op_sel_hi:[0,1,1]
	v_pk_fma_f32 v[104:105], v[142:143], v[198:199], v[104:105] op_sel_hi:[0,1,1]
	v_pk_fma_f32 v[100:101], v[142:143], v[30:31], v[18:19] op_sel_hi:[0,1,1]
	ds_read_u16 v16, v139 offset:256
	ds_read_u16 v17, v139 offset:260
	ds_read_u16 v24, v139 offset:264
	ds_read_u16 v26, v139 offset:268
	s_waitcnt lgkmcnt(3)
	v_and_b32_e32 v16, 0x3fff, v16
	s_waitcnt lgkmcnt(2)
	v_and_b32_e32 v18, 0x3fff, v17
	v_lshlrev_b32_sdwa v68, v231, v16 dst_sel:DWORD dst_unused:UNUSED_PAD src0_sel:DWORD src1_sel:WORD_0
	v_lshl_add_u64 v[16:17], v[78:79], 0, v[68:69]
	v_lshlrev_b32_sdwa v68, v231, v18 dst_sel:DWORD dst_unused:UNUSED_PAD src0_sel:DWORD src1_sel:WORD_0
	s_waitcnt lgkmcnt(1)
	v_and_b32_e32 v24, 0x3fff, v24
	v_lshl_add_u64 v[18:19], v[78:79], 0, v[68:69]
	v_lshlrev_b32_sdwa v68, v231, v24 dst_sel:DWORD dst_unused:UNUSED_PAD src0_sel:DWORD src1_sel:WORD_0
	s_waitcnt lgkmcnt(0)
	v_and_b32_e32 v26, 0x3fff, v26
	v_lshl_add_u64 v[24:25], v[78:79], 0, v[68:69]
	v_lshlrev_b32_sdwa v68, v231, v26 dst_sel:DWORD dst_unused:UNUSED_PAD src0_sel:DWORD src1_sel:WORD_0
	v_lshl_add_u64 v[26:27], v[78:79], 0, v[68:69]
	global_load_dwordx4 v[20:23], v[16:17], off
	s_nop 0
	global_load_dwordx4 v[16:19], v[18:19], off
	s_nop 0
	global_load_dwordx4 v[28:31], v[24:25], off
	s_nop 0
	global_load_dwordx4 v[24:27], v[26:27], off
	ds_read2_b32 v[102:103], v155 offset0:128 offset1:130
	ds_read2_b32 v[98:99], v155 offset0:132 offset1:134
	s_waitcnt vmcnt(11)
	v_cvt_f32_i32_sdwa v143, sext(v12) dst_sel:DWORD dst_unused:UNUSED_PAD src0_sel:BYTE_1
	v_cvt_f32_i32_sdwa v142, sext(v12) dst_sel:DWORD dst_unused:UNUSED_PAD src0_sel:BYTE_0
	s_waitcnt vmcnt(10)
	v_cvt_f32_i32_sdwa v145, sext(v4) dst_sel:DWORD dst_unused:UNUSED_PAD src0_sel:BYTE_1
	v_cvt_f32_i32_sdwa v144, sext(v4) dst_sel:DWORD dst_unused:UNUSED_PAD src0_sel:BYTE_0
	s_waitcnt vmcnt(9)
	v_cvt_f32_i32_sdwa v147, sext(v8) dst_sel:DWORD dst_unused:UNUSED_PAD src0_sel:BYTE_1
	v_cvt_f32_i32_sdwa v146, sext(v8) dst_sel:DWORD dst_unused:UNUSED_PAD src0_sel:BYTE_0
	s_waitcnt vmcnt(8)
	v_cvt_f32_i32_sdwa v149, sext(v0) dst_sel:DWORD dst_unused:UNUSED_PAD src0_sel:BYTE_1
	v_cvt_f32_i32_sdwa v148, sext(v0) dst_sel:DWORD dst_unused:UNUSED_PAD src0_sel:BYTE_0
	v_cvt_f32_i32_sdwa v157, sext(v12) dst_sel:DWORD dst_unused:UNUSED_PAD src0_sel:BYTE_3
	v_cvt_f32_i32_sdwa v156, sext(v12) dst_sel:DWORD dst_unused:UNUSED_PAD src0_sel:BYTE_2
	v_cvt_f32_i32_sdwa v159, sext(v4) dst_sel:DWORD dst_unused:UNUSED_PAD src0_sel:BYTE_3
	v_cvt_f32_i32_sdwa v158, sext(v4) dst_sel:DWORD dst_unused:UNUSED_PAD src0_sel:BYTE_2
	v_cvt_f32_i32_sdwa v161, sext(v8) dst_sel:DWORD dst_unused:UNUSED_PAD src0_sel:BYTE_3
	v_cvt_f32_i32_sdwa v160, sext(v8) dst_sel:DWORD dst_unused:UNUSED_PAD src0_sel:BYTE_2
	v_cvt_f32_i32_sdwa v163, sext(v0) dst_sel:DWORD dst_unused:UNUSED_PAD src0_sel:BYTE_3
	v_cvt_f32_i32_sdwa v162, sext(v0) dst_sel:DWORD dst_unused:UNUSED_PAD src0_sel:BYTE_2
	v_cvt_f32_i32_sdwa v165, sext(v13) dst_sel:DWORD dst_unused:UNUSED_PAD src0_sel:BYTE_1
	v_cvt_f32_i32_sdwa v164, sext(v13) dst_sel:DWORD dst_unused:UNUSED_PAD src0_sel:BYTE_0
	v_cvt_f32_i32_sdwa v167, sext(v5) dst_sel:DWORD dst_unused:UNUSED_PAD src0_sel:BYTE_1
	v_cvt_f32_i32_sdwa v166, sext(v5) dst_sel:DWORD dst_unused:UNUSED_PAD src0_sel:BYTE_0
	v_cvt_f32_i32_sdwa v169, sext(v9) dst_sel:DWORD dst_unused:UNUSED_PAD src0_sel:BYTE_1
	v_cvt_f32_i32_sdwa v168, sext(v9) dst_sel:DWORD dst_unused:UNUSED_PAD src0_sel:BYTE_0
	v_cvt_f32_i32_sdwa v171, sext(v1) dst_sel:DWORD dst_unused:UNUSED_PAD src0_sel:BYTE_1
	v_cvt_f32_i32_sdwa v170, sext(v1) dst_sel:DWORD dst_unused:UNUSED_PAD src0_sel:BYTE_0
	v_cvt_f32_i32_sdwa v173, sext(v13) dst_sel:DWORD dst_unused:UNUSED_PAD src0_sel:BYTE_3
	v_cvt_f32_i32_sdwa v172, sext(v13) dst_sel:DWORD dst_unused:UNUSED_PAD src0_sel:BYTE_2
	v_cvt_f32_i32_sdwa v13, sext(v5) dst_sel:DWORD dst_unused:UNUSED_PAD src0_sel:BYTE_3
	v_cvt_f32_i32_sdwa v12, sext(v5) dst_sel:DWORD dst_unused:UNUSED_PAD src0_sel:BYTE_2
	v_cvt_f32_i32_sdwa v5, sext(v9) dst_sel:DWORD dst_unused:UNUSED_PAD src0_sel:BYTE_3
	v_cvt_f32_i32_sdwa v4, sext(v9) dst_sel:DWORD dst_unused:UNUSED_PAD src0_sel:BYTE_2
	v_cvt_f32_i32_sdwa v9, sext(v1) dst_sel:DWORD dst_unused:UNUSED_PAD src0_sel:BYTE_3
	v_cvt_f32_i32_sdwa v8, sext(v1) dst_sel:DWORD dst_unused:UNUSED_PAD src0_sel:BYTE_2
	v_cvt_f32_i32_sdwa v1, sext(v14) dst_sel:DWORD dst_unused:UNUSED_PAD src0_sel:BYTE_1
	v_cvt_f32_i32_sdwa v0, sext(v14) dst_sel:DWORD dst_unused:UNUSED_PAD src0_sel:BYTE_0
	v_cvt_f32_i32_sdwa v181, sext(v14) dst_sel:DWORD dst_unused:UNUSED_PAD src0_sel:BYTE_3
	v_cvt_f32_i32_sdwa v180, sext(v14) dst_sel:DWORD dst_unused:UNUSED_PAD src0_sel:BYTE_2
	v_cvt_f32_i32_sdwa v189, sext(v15) dst_sel:DWORD dst_unused:UNUSED_PAD src0_sel:BYTE_1
	v_cvt_f32_i32_sdwa v188, sext(v15) dst_sel:DWORD dst_unused:UNUSED_PAD src0_sel:BYTE_0
	v_cvt_f32_i32_sdwa v197, sext(v15) dst_sel:DWORD dst_unused:UNUSED_PAD src0_sel:BYTE_3
	v_cvt_f32_i32_sdwa v196, sext(v15) dst_sel:DWORD dst_unused:UNUSED_PAD src0_sel:BYTE_2
	v_cvt_f32_i32_sdwa v175, sext(v6) dst_sel:DWORD dst_unused:UNUSED_PAD src0_sel:BYTE_1
	v_cvt_f32_i32_sdwa v174, sext(v6) dst_sel:DWORD dst_unused:UNUSED_PAD src0_sel:BYTE_0
	v_cvt_f32_i32_sdwa v183, sext(v6) dst_sel:DWORD dst_unused:UNUSED_PAD src0_sel:BYTE_3
	v_cvt_f32_i32_sdwa v182, sext(v6) dst_sel:DWORD dst_unused:UNUSED_PAD src0_sel:BYTE_2
	v_cvt_f32_i32_sdwa v191, sext(v7) dst_sel:DWORD dst_unused:UNUSED_PAD src0_sel:BYTE_1
	v_cvt_f32_i32_sdwa v190, sext(v7) dst_sel:DWORD dst_unused:UNUSED_PAD src0_sel:BYTE_0
	v_cvt_f32_i32_sdwa v15, sext(v7) dst_sel:DWORD dst_unused:UNUSED_PAD src0_sel:BYTE_3
	v_cvt_f32_i32_sdwa v14, sext(v7) dst_sel:DWORD dst_unused:UNUSED_PAD src0_sel:BYTE_2
	v_cvt_f32_i32_sdwa v177, sext(v10) dst_sel:DWORD dst_unused:UNUSED_PAD src0_sel:BYTE_1
	v_cvt_f32_i32_sdwa v176, sext(v10) dst_sel:DWORD dst_unused:UNUSED_PAD src0_sel:BYTE_0
	v_cvt_f32_i32_sdwa v185, sext(v10) dst_sel:DWORD dst_unused:UNUSED_PAD src0_sel:BYTE_3
	v_cvt_f32_i32_sdwa v184, sext(v10) dst_sel:DWORD dst_unused:UNUSED_PAD src0_sel:BYTE_2
	v_cvt_f32_i32_sdwa v193, sext(v11) dst_sel:DWORD dst_unused:UNUSED_PAD src0_sel:BYTE_1
	v_cvt_f32_i32_sdwa v192, sext(v11) dst_sel:DWORD dst_unused:UNUSED_PAD src0_sel:BYTE_0
	v_cvt_f32_i32_sdwa v7, sext(v11) dst_sel:DWORD dst_unused:UNUSED_PAD src0_sel:BYTE_3
	v_cvt_f32_i32_sdwa v6, sext(v11) dst_sel:DWORD dst_unused:UNUSED_PAD src0_sel:BYTE_2
	v_cvt_f32_i32_sdwa v179, sext(v2) dst_sel:DWORD dst_unused:UNUSED_PAD src0_sel:BYTE_1
	v_cvt_f32_i32_sdwa v178, sext(v2) dst_sel:DWORD dst_unused:UNUSED_PAD src0_sel:BYTE_0
	v_cvt_f32_i32_sdwa v187, sext(v2) dst_sel:DWORD dst_unused:UNUSED_PAD src0_sel:BYTE_3
	v_cvt_f32_i32_sdwa v186, sext(v2) dst_sel:DWORD dst_unused:UNUSED_PAD src0_sel:BYTE_2
	v_cvt_f32_i32_sdwa v195, sext(v3) dst_sel:DWORD dst_unused:UNUSED_PAD src0_sel:BYTE_1
	v_cvt_f32_i32_sdwa v194, sext(v3) dst_sel:DWORD dst_unused:UNUSED_PAD src0_sel:BYTE_0
	v_cvt_f32_i32_sdwa v11, sext(v3) dst_sel:DWORD dst_unused:UNUSED_PAD src0_sel:BYTE_3
	v_cvt_f32_i32_sdwa v10, sext(v3) dst_sel:DWORD dst_unused:UNUSED_PAD src0_sel:BYTE_2
	v_pk_fma_f32 v[2:3], v[58:59], v[142:143], v[96:97] op_sel_hi:[0,1,1]
	v_pk_fma_f32 v[94:95], v[58:59], v[156:157], v[94:95] op_sel_hi:[0,1,1]
	v_pk_fma_f32 v[62:63], v[58:59], v[164:165], v[62:63] op_sel_hi:[0,1,1]
	v_pk_fma_f32 v[60:61], v[58:59], v[172:173], v[60:61] op_sel_hi:[0,1,1]
	v_pk_fma_f32 v[0:1], v[58:59], v[0:1], v[56:57] op_sel_hi:[0,1,1]
	v_pk_fma_f32 v[52:53], v[58:59], v[180:181], v[52:53] op_sel_hi:[0,1,1]
	v_pk_fma_f32 v[48:49], v[58:59], v[188:189], v[48:49] op_sel_hi:[0,1,1]
	v_pk_fma_f32 v[50:51], v[58:59], v[196:197], v[50:51] op_sel_hi:[0,1,1]
	v_pk_fma_f32 v[2:3], v[140:141], v[144:145], v[2:3] op_sel_hi:[0,1,1]
	v_pk_fma_f32 v[56:57], v[140:141], v[158:159], v[94:95] op_sel_hi:[0,1,1]
	v_pk_fma_f32 v[58:59], v[140:141], v[166:167], v[62:63] op_sel_hi:[0,1,1]
	v_pk_fma_f32 v[12:13], v[140:141], v[12:13], v[60:61] op_sel_hi:[0,1,1]
	v_pk_fma_f32 v[0:1], v[140:141], v[174:175], v[0:1] op_sel_hi:[0,1,1]
	v_pk_fma_f32 v[52:53], v[140:141], v[182:183], v[52:53] op_sel_hi:[0,1,1]
	v_pk_fma_f32 v[48:49], v[140:141], v[190:191], v[48:49] op_sel_hi:[0,1,1]
	v_pk_fma_f32 v[14:15], v[140:141], v[14:15], v[50:51] op_sel_hi:[0,1,1]
	v_pk_fma_f32 v[2:3], v[54:55], v[146:147], v[2:3] op_sel_hi:[0,1,1]
	v_pk_fma_f32 v[50:51], v[54:55], v[160:161], v[56:57] op_sel_hi:[0,1,1]
	v_pk_fma_f32 v[56:57], v[54:55], v[168:169], v[58:59] op_sel_hi:[0,1,1]
	v_pk_fma_f32 v[4:5], v[54:55], v[4:5], v[12:13] op_sel_hi:[0,1,1]
	v_pk_fma_f32 v[0:1], v[54:55], v[176:177], v[0:1] op_sel_hi:[0,1,1]
	v_pk_fma_f32 v[12:13], v[54:55], v[184:185], v[52:53] op_sel_hi:[0,1,1]
	v_pk_fma_f32 v[48:49], v[54:55], v[192:193], v[48:49] op_sel_hi:[0,1,1]
	v_pk_fma_f32 v[6:7], v[54:55], v[6:7], v[14:15] op_sel_hi:[0,1,1]
	v_pk_fma_f32 v[96:97], v[138:139], v[148:149], v[2:3] op_sel_hi:[0,1,1]
	v_pk_fma_f32 v[94:95], v[138:139], v[162:163], v[50:51] op_sel_hi:[0,1,1]
	v_pk_fma_f32 v[62:63], v[138:139], v[170:171], v[56:57] op_sel_hi:[0,1,1]
	v_pk_fma_f32 v[60:61], v[138:139], v[8:9], v[4:5] op_sel_hi:[0,1,1]
	v_pk_fma_f32 v[56:57], v[138:139], v[178:179], v[0:1] op_sel_hi:[0,1,1]
	v_pk_fma_f32 v[52:53], v[138:139], v[186:187], v[12:13] op_sel_hi:[0,1,1]
	v_pk_fma_f32 v[48:49], v[138:139], v[194:195], v[48:49] op_sel_hi:[0,1,1]
	v_pk_fma_f32 v[50:51], v[138:139], v[10:11], v[6:7] op_sel_hi:[0,1,1]
	ds_read_u16 v0, v139 offset:512
	ds_read_u16 v1, v139 offset:516
	ds_read_u16 v2, v139 offset:520
	ds_read_u16 v3, v139 offset:524
	v_add_u32_e32 v58, 0x400, v155
	s_waitcnt lgkmcnt(3)
; #define LAS __attribute__((address_space(3)))
; __device__ __forceinline__ void phase10(const Args& a, LAS unsigned char* lds, int tid, int wave, int lane, int vcu, int G, int emask, bool probe) {
;     ...
;         for (int tk = 0; tk < GTK; ++tk) {
; #pragma unroll
;             for (int q = 0; q < 4; ++q) { f32x4 s4;
; #pragma unroll
;                 for (int e = 0; e < 4; ++e) { s4[e] = y[tk][4 * q + e] + __shfl_xor(y[tk][4 * q + e], 32); y[tk][4 * q + e] = 0.f; }
;                 if (hl == 0) *(LAS f32x4*)(YS + (tk * 32 + lq) * 16 + 4 * q) = s4; } }
	v_and_b32_e32 v0, 0x3fff, v0
	s_waitcnt lgkmcnt(2)
	v_and_b32_e32 v4, 0x3fff, v1
	v_lshlrev_b32_sdwa v68, v231, v0 dst_sel:DWORD dst_unused:UNUSED_PAD src0_sel:DWORD src1_sel:WORD_0
	s_waitcnt lgkmcnt(1)
	v_and_b32_e32 v5, 0x3fff, v2
	v_lshl_add_u64 v[0:1], v[78:79], 0, v[68:69]
	v_lshlrev_b32_sdwa v68, v231, v4 dst_sel:DWORD dst_unused:UNUSED_PAD src0_sel:DWORD src1_sel:WORD_0
	s_waitcnt lgkmcnt(0)
	v_and_b32_e32 v8, 0x3fff, v3
	v_lshl_add_u64 v[2:3], v[78:79], 0, v[68:69]
	v_lshlrev_b32_sdwa v68, v231, v5 dst_sel:DWORD dst_unused:UNUSED_PAD src0_sel:DWORD src1_sel:WORD_0
	global_load_dwordx4 v[12:15], v[0:1], off
	global_load_dwordx4 v[4:7], v[2:3], off
	v_lshl_add_u64 v[0:1], v[78:79], 0, v[68:69]
	v_lshlrev_b32_sdwa v68, v231, v8 dst_sel:DWORD dst_unused:UNUSED_PAD src0_sel:DWORD src1_sel:WORD_0
	v_lshl_add_u64 v[2:3], v[78:79], 0, v[68:69]
	global_load_dwordx4 v[8:11], v[0:1], off
	s_nop 0
	global_load_dwordx4 v[0:3], v[2:3], off
	ds_read2_b32 v[54:55], v58 offset0:4 offset1:6
	ds_read2_b32 v[58:59], v58 offset1:2
	s_add_i32 s10, s10, 8
	v_add_u32_e32 v155, 32, v155
	v_add_u32_e32 v139, 16, v139
	v_mov_b32_e32 v146, v121
	v_mov_b32_e32 v148, v119
	v_mov_b32_e32 v142, v99
	v_mov_b32_e32 v144, v103
	s_cmpk_gt_u32 s10, 0x6f
	s_waitcnt lgkmcnt(1)
	v_mov_b32_e32 v138, v55
	s_waitcnt lgkmcnt(0)
	v_mov_b32_e32 v140, v59
	s_cbranch_scc0 .LBB0_1726
	s_waitcnt vmcnt(11)
	v_cvt_f32_i32_sdwa v139, sext(v40) dst_sel:DWORD dst_unused:UNUSED_PAD src0_sel:BYTE_1
	v_cvt_f32_i32_sdwa v138, sext(v40) dst_sel:DWORD dst_unused:UNUSED_PAD src0_sel:BYTE_0
	s_waitcnt vmcnt(10)
	v_cvt_f32_i32_sdwa v141, sext(v32) dst_sel:DWORD dst_unused:UNUSED_PAD src0_sel:BYTE_1
	v_cvt_f32_i32_sdwa v140, sext(v32) dst_sel:DWORD dst_unused:UNUSED_PAD src0_sel:BYTE_0
	s_waitcnt vmcnt(8)
	v_cvt_f32_i32_sdwa v143, sext(v36) dst_sel:DWORD dst_unused:UNUSED_PAD src0_sel:BYTE_1
	v_pk_fma_f32 v[136:137], v[118:119], v[138:139], v[136:137] op_sel_hi:[0,1,1]
	v_cvt_f32_i32_sdwa v139, sext(v44) dst_sel:DWORD dst_unused:UNUSED_PAD src0_sel:BYTE_1
	v_cvt_f32_i32_sdwa v138, sext(v44) dst_sel:DWORD dst_unused:UNUSED_PAD src0_sel:BYTE_0
	v_cvt_f32_i32_sdwa v142, sext(v36) dst_sel:DWORD dst_unused:UNUSED_PAD src0_sel:BYTE_0
	v_mov_b32_e32 v68, v119
	v_pk_fma_f32 v[136:137], v[68:69], v[140:141], v[136:137] op_sel_hi:[0,1,1]
	v_pk_fma_f32 v[136:137], v[120:121], v[138:139], v[136:137] op_sel_hi:[0,1,1]
	v_mov_b32_e32 v138, v121
	v_cvt_f32_i32_sdwa v141, sext(v40) dst_sel:DWORD dst_unused:UNUSED_PAD src0_sel:BYTE_3
	v_cvt_f32_i32_sdwa v140, sext(v40) dst_sel:DWORD dst_unused:UNUSED_PAD src0_sel:BYTE_2
	v_pk_fma_f32 v[136:137], v[138:139], v[142:143], v[136:137] op_sel_hi:[0,1,1]
	v_cvt_f32_i32_sdwa v143, sext(v32) dst_sel:DWORD dst_unused:UNUSED_PAD src0_sel:BYTE_3
	v_cvt_f32_i32_sdwa v142, sext(v32) dst_sel:DWORD dst_unused:UNUSED_PAD src0_sel:BYTE_2
	v_cvt_f32_i32_sdwa v145, sext(v44) dst_sel:DWORD dst_unused:UNUSED_PAD src0_sel:BYTE_3
	v_cvt_f32_i32_sdwa v144, sext(v44) dst_sel:DWORD dst_unused:UNUSED_PAD src0_sel:BYTE_2
	v_cvt_f32_i32_sdwa v147, sext(v36) dst_sel:DWORD dst_unused:UNUSED_PAD src0_sel:BYTE_3
	v_cvt_f32_i32_sdwa v146, sext(v36) dst_sel:DWORD dst_unused:UNUSED_PAD src0_sel:BYTE_2
	v_pk_fma_f32 v[134:135], v[118:119], v[140:141], v[134:135] op_sel_hi:[0,1,1]
	v_pk_fma_f32 v[134:135], v[68:69], v[142:143], v[134:135] op_sel_hi:[0,1,1]
	v_pk_fma_f32 v[134:135], v[120:121], v[144:145], v[134:135] op_sel_hi:[0,1,1]
	v_pk_fma_f32 v[134:135], v[138:139], v[146:147], v[134:135] op_sel_hi:[0,1,1]
	s_barrier
	ds_bpermute_b32 v138, v216, v136
	ds_bpermute_b32 v139, v216, v137
	ds_bpermute_b32 v140, v216, v134
	ds_bpermute_b32 v141, v216, v135
	v_add_u32_e32 v68, s40, v70
	s_and_saveexec_b64 s[10:11], s[6:7]
	s_cbranch_execz .LBB0_1729
	s_waitcnt lgkmcnt(0)
	v_pk_add_f32 v[140:141], v[134:135], v[140:141]
	v_pk_add_f32 v[138:139], v[136:137], v[138:139]
	ds_write_b128 v68, v[138:141] offset:32768
